# v20 + grid barrier between prologue and norm phase replaced by an adaLN-done counter (write-through mod stores, one atomic per producer block, thread-0 poll + L1 invalidate)
# speedup vs baseline: 1.0161x; 1.0062x over previous
; __device__ __forceinline__ void p0_prologue(const Args& a, LAS unsigned char* lds) {
;     ...
;         if (tid < 160) { const int v = tid >> 5, c = tid & 31; float t = 0.f;
; #pragma unroll
;             for (int q = 0; q < 8; ++q) t += red[(q * 5 + v) * 32 + c];
;             ((float*)(ws + WS_MOD))[(layer * 5 + v) * 3072 + n0 + c] = t + a.in[6][layer * 3072 + n0 + c]; }
;         __syncthreads();
.LBB0_21:
	s_or_b64 exec, exec, s[0:1]
	s_movk_i32 s0, 0xa0
	v_cmp_gt_u32_e32 vcc, s0, v192
	s_waitcnt lgkmcnt(0)
	s_barrier
	s_and_saveexec_b64 s[0:1], vcc
	s_cbranch_execz .LBB0_23
	s_mul_i32 s3, s4, 0xc00
	v_and_b32_e32 v8, 31, v192
	s_add_i32 s3, s3, s2
	v_or_b32_e32 v2, s3, v8
	v_mov_b32_e32 v0, s48
	v_mov_b32_e32 v1, s49
	v_ashrrev_i32_e32 v3, 31, v2
	v_lshl_add_u64 v[0:1], v[2:3], 2, v[0:1]
	global_load_dword v10, v[0:1], off
	v_lshrrev_b32_e32 v0, 5, v192
	v_lshlrev_b32_e32 v2, 2, v8
	v_lshlrev_b32_e32 v3, 7, v0
	v_mad_u64_u32 v[0:1], s[4:5], s4, 5, v[0:1]
	s_movk_i32 s3, 0xc00
	v_add3_u32 v1, 0, v2, v3
	v_mul_lo_u32 v0, v0, s3
	v_add_u32_e32 v2, 0x5000, v1
	v_add_u32_e32 v3, 0x5400, v1
	v_add_u32_e32 v4, 0x5a00, v1
	v_add_u32_e32 v6, 0x5e00, v1
	v_add_u32_e32 v9, s2, v0
	ds_read2_b32 v[0:1], v2 offset1:160
	ds_read2_b32 v[2:3], v3 offset0:64 offset1:224
	ds_read2_b32 v[4:5], v4 offset1:160
	ds_read2_b32 v[6:7], v6 offset0:64 offset1:224
	v_or_b32_e32 v8, v9, v8
	s_waitcnt lgkmcnt(3)
	v_add_f32_e32 v0, 0, v0
	v_add_f32_e32 v0, v0, v1
	s_waitcnt lgkmcnt(2)
	v_add_f32_e32 v0, v0, v2
	v_add_f32_e32 v0, v0, v3
	s_waitcnt lgkmcnt(1)
	v_add_f32_e32 v0, v0, v4
	v_add_f32_e32 v0, v0, v5
	s_waitcnt lgkmcnt(0)
	v_add_f32_e32 v0, v0, v6
	v_ashrrev_i32_e32 v9, 31, v8
	v_add_f32_e32 v0, v0, v7
	s_waitcnt vmcnt(0)
	v_add_f32_e32 v2, v0, v10
	v_lshl_add_u64 v[0:1], v[8:9], 2, s[30:31]
	global_store_dword v[0:1], v2, off sc1
.LBB0_23:
	s_or_b64 exec, exec, s[0:1]
	s_waitcnt vmcnt(0)
	s_barrier
	s_and_saveexec_b64 s[96:97], s[10:11]
	s_cbranch_execz .Lada_flag_done
	s_add_u32 s98, s30, 0x236b0
	s_addc_u32 s99, s31, 0
	v_mov_b32_e32 v252, 0
	v_mov_b32_e32 v253, 1
	global_atomic_add v252, v253, s[98:99]
.Lada_flag_done:
	s_or_b64 exec, exec, s[96:97]
	s_and_b32 s0, s12, -16
	s_cmpk_lg_i32 s0, 0xc0
	v_lshl_add_u32 v8, s12, 9, v192
	s_cbranch_scc0 .LBB0_26

; __device__ __forceinline__ unsigned xb_ld(unsigned* p)              { return __hip_atomic_load(p, __ATOMIC_RELAXED, __HIP_MEMORY_SCOPE_AGENT); }
; __device__ __forceinline__ unsigned xb_add(unsigned* p, unsigned v) { return __hip_atomic_fetch_add(p, v, __ATOMIC_RELAXED, __HIP_MEMORY_SCOPE_AGENT); }
; #define XB_SPIN(cond, bar) do { unsigned _sp = 0; while (cond) { __builtin_amdgcn_s_sleep(1); \
;     if ((++_sp & 255u) == 0u) { if (xb_ld(&(bar)[XB_TMO])) break; if (_sp > XB_SPIN_CAP) { atomicAdd(&(bar)[XB_TMO], 1u); break; } } } } while (0)
; __device__ __forceinline__ void xcd_barrier(const XcdBarrier& b) {
;     asm volatile("s_waitcnt vmcnt(0)" ::: "memory");
;     __syncthreads();
;     if (threadIdx.x == 0) {
;         unsigned* bar = b.bar;
;         __builtin_amdgcn_s_waitcnt(0);
;         unsigned nloc = b.st[0], nx = b.st[1];
;         if (nloc == 0u) { xcd_barrier_complete(bar, b.x, nloc, nx); b.st[0] = nloc; b.st[1] = nx; }
;         const unsigned old = xb_add(&bar[XB_XSUB(b.x)], 1u);
;         const unsigned gen = old / nloc;
;         if (old + 1u == (gen + 1u) * nloc) {
;             __builtin_amdgcn_fence(__ATOMIC_RELEASE, "agent");
;             asm volatile("s_waitcnt vmcnt(0)" ::: "memory");
;             const unsigned og = xb_add(&bar[XB_TOP], 1u);
;             const unsigned tg = og / nx;
;             if (og + 1u == (tg + 1u) * nx) xb_add(&bar[XB_TOPGEN], 1u);
;             else XB_SPIN(xb_ld(&bar[XB_TOPGEN]) == tg, bar);
;             __builtin_amdgcn_fence(__ATOMIC_ACQUIRE, "agent");
;             xb_add(&bar[XB_XGEN(b.x)], 1u);
;             asm volatile("s_waitcnt vmcnt(0)" ::: "memory");
;         } else {
;             XB_SPIN(xb_ld(&bar[XB_XGEN(b.x)]) == gen, bar);
;             __builtin_amdgcn_fence(__ATOMIC_ACQUIRE, "agent");
;             asm volatile("s_waitcnt vmcnt(0)" ::: "memory");
;         }
;     }
;     __syncthreads();
.LBB0_52:
	s_cmp_gt_i32 s69, 1
	s_cselect_b64 s[0:1], -1, 0
	s_and_b64 s[2:3], s[8:9], s[0:1]
	s_andn2_b64 vcc, exec, s[2:3]
	s_cbranch_vccnz .LBB0_106
	s_waitcnt vmcnt(0)
	s_waitcnt lgkmcnt(0)
	s_barrier
	s_and_saveexec_b64 s[2:3], s[10:11]
	s_cbranch_execz .LBB0_105
	s_add_u32 s98, s30, 0x236b0
	s_addc_u32 s99, s31, 0
	v_mov_b32_e32 v252, 0
	s_mov_b32 s100, 0
.Lseam0_spin:
	global_load_dword v253, v252, s[98:99] sc1
	s_waitcnt vmcnt(0)
	v_readfirstlane_b32 s101, v253
	s_nop 3
	s_cmpk_ge_u32 s101, 0xc0
	s_cbranch_scc1 .Lseam0_ok
	s_sleep 1
	s_add_u32 s100, s100, 1
	s_cmp_lt_u32 s100, 0x40000
	s_cbranch_scc1 .Lseam0_spin
.Lseam0_ok:
	buffer_inv sc1
	s_waitcnt vmcnt(0)

; __global__ void __launch_bounds__(512, 2) fwd_megakernel(Args a) {
	.amdhsa_kernel _Z14fwd_megakernel4Args
		.amdhsa_group_segment_fixed_size 0
		.amdhsa_private_segment_fixed_size 0
		.amdhsa_kernarg_size 464
		.amdhsa_user_sgpr_count 2
		.amdhsa_user_sgpr_dispatch_ptr 0
		.amdhsa_user_sgpr_queue_ptr 0
		.amdhsa_user_sgpr_kernarg_segment_ptr 1
		.amdhsa_user_sgpr_dispatch_id 0
		.amdhsa_user_sgpr_kernarg_preload_length 0
		.amdhsa_user_sgpr_kernarg_preload_offset 0
		.amdhsa_user_sgpr_private_segment_size 0
		.amdhsa_uses_dynamic_stack 0
		.amdhsa_enable_private_segment 0
		.amdhsa_system_sgpr_workgroup_id_x 1
		.amdhsa_system_sgpr_workgroup_id_y 0
		.amdhsa_system_sgpr_workgroup_id_z 0
		.amdhsa_system_sgpr_workgroup_info 0
		.amdhsa_system_vgpr_workitem_id 2
		.amdhsa_next_free_vgpr 256
		.amdhsa_next_free_sgpr 102
		.amdhsa_accum_offset 256
		.amdhsa_reserve_vcc 1
		.amdhsa_float_round_mode_32 0
		.amdhsa_float_round_mode_16_64 0
		.amdhsa_float_denorm_mode_32 3
		.amdhsa_float_denorm_mode_16_64 3
		.amdhsa_dx10_clamp 1
		.amdhsa_ieee_mode 1
		.amdhsa_fp16_overflow 0
		.amdhsa_tg_split 0
		.amdhsa_exception_fp_ieee_invalid_op 0
		.amdhsa_exception_fp_denorm_src 0
		.amdhsa_exception_fp_ieee_div_zero 0
		.amdhsa_exception_fp_ieee_overflow 0
		.amdhsa_exception_fp_ieee_underflow 0
		.amdhsa_exception_fp_ieee_inexact 0
		.amdhsa_exception_int_div_zero 0
	.end_amdhsa_kernel

; __global__ void __launch_bounds__(512, 2) fwd_megakernel(Args a) {
amdhsa.kernels:
  - .agpr_count:     0
    .args:
      - .offset:         0
        .size:           208
        .value_kind:     by_value
      - .offset:         208
        .size:           4
        .value_kind:     hidden_block_count_x
      - .offset:         212
        .size:           4
        .value_kind:     hidden_block_count_y
      - .offset:         216
        .size:           4
        .value_kind:     hidden_block_count_z
      - .offset:         220
        .size:           2
        .value_kind:     hidden_group_size_x
      - .offset:         222
        .size:           2
        .value_kind:     hidden_group_size_y
      - .offset:         224
        .size:           2
        .value_kind:     hidden_group_size_z
      - .offset:         226
        .size:           2
        .value_kind:     hidden_remainder_x
      - .offset:         228
        .size:           2
        .value_kind:     hidden_remainder_y
      - .offset:         230
        .size:           2
        .value_kind:     hidden_remainder_z
      - .offset:         248
        .size:           8
        .value_kind:     hidden_global_offset_x
      - .offset:         256
        .size:           8
        .value_kind:     hidden_global_offset_y
      - .offset:         264
        .size:           8
        .value_kind:     hidden_global_offset_z
      - .offset:         272
        .size:           2
        .value_kind:     hidden_grid_dims
      - .offset:         296
        .size:           8
        .value_kind:     hidden_multigrid_sync_arg
      - .offset:         328
        .size:           4
        .value_kind:     hidden_dynamic_lds_size
    .group_segment_fixed_size: 0
    .kernarg_segment_align: 8
    .kernarg_segment_size: 464
    .language:       OpenCL C
    .language_version:
      - 2
      - 0
    .max_flat_workgroup_size: 512
    .name:           _Z14fwd_megakernel4Args
    .private_segment_fixed_size: 0
    .sgpr_count:     108
    .sgpr_spill_count: 0
    .symbol:         _Z14fwd_megakernel4Args.kd
    .uniform_work_group_size: 1
    .uses_dynamic_stack: false
    .vgpr_count:     256
    .vgpr_spill_count: 0
    .wavefront_size: 64
